# w_in weight tiles converted in P1 by workgroups 172..243 (no unit in the last GEMM round)
# baseline (speedup 1.0000x reference)
; __device__ __forceinline__ void convert_weights(CArgsP a, LAS unsigned char* lds, int wave, int lane, int which, int gb, int NGB) {
;     ...
;     for (int it = gb; it < NIT; it += NGB) {
;         int r = it;
;         if (r < I0) { const int pn = r >> 4, kb = r & 15;
;             convert_tile(which == 0 ? a->in[8] : a->in[28], 1024, 5632, which == 0 ? a->in[7] : a->in[27], (bf16_t*)(ws + (which == 0 ? WS_W1I : WS_W2I)), pn, 64 * kb, 0, lds, wave, lane); continue; }
;         r -= I0;
;         if (r < I1) { const int pn = r / 44, kb = r % 44; convert_tile(which == 0 ? a->in[9] : a->in[29], DFF, 1024, nullptr, (bf16_t*)(ws + (which == 0 ? WS_W1O : WS_W2O)), pn, 64 * kb, 1, lds, wave, lane); continue; }
;         r -= I1;
;         if (which == 0) { const int pn = r >> 4, kb = r & 15; convert_tile(a->in[11], 1024, 3336, a->in[10], (bf16_t*)(ws + WS_WIN), pn, 64 * kb, 2, lds, wave, lane); }
; __global__ void __launch_bounds__(512, 2) mega_fwd(Args a_unused) {
;     ...
;       if (bx >= G - 4) {
.LBB0_124:
	s_add_i32 s77, s60, -4
	s_cmp_ge_i32 s2, s77
	s_cselect_b64 s[80:81], -1, 0
	s_cmp_lt_i32 s2, s77
	s_cbranch_scc0 .Lp1_tail
	s_cmpk_lt_i32 s2, 0xac
	s_cbranch_scc1 .LBB0_225
	s_cmpk_gt_i32 s2, 0xf3
	s_cbranch_scc1 .LBB0_225
	s_cmpk_lg_i32 s60, 0x100
	s_cbranch_scc1 .LBB0_225
	v_writelane_b32 v253, s0, 0
	v_writelane_b32 v253, s1, 1
	v_writelane_b32 v253, s2, 2
	v_writelane_b32 v253, s3, 3
	v_writelane_b32 v253, s4, 4
	v_writelane_b32 v253, s5, 5
	v_writelane_b32 v253, s6, 6
	v_writelane_b32 v253, s7, 7
	v_writelane_b32 v253, s12, 8
	v_writelane_b32 v253, s13, 9
	v_writelane_b32 v253, s14, 10
	v_writelane_b32 v253, s15, 11
	v_writelane_b32 v253, s16, 12
	v_writelane_b32 v253, s17, 13
	v_writelane_b32 v253, s18, 14
	v_writelane_b32 v253, s19, 15
	v_writelane_b32 v253, s20, 16
	v_writelane_b32 v253, s21, 17
	v_writelane_b32 v253, s22, 18
	v_writelane_b32 v253, s23, 19
	v_writelane_b32 v253, s24, 20
	v_writelane_b32 v253, s25, 21
	v_writelane_b32 v253, s26, 22
	v_writelane_b32 v253, s27, 23
	v_writelane_b32 v253, s28, 24
	v_writelane_b32 v253, s29, 25
	v_writelane_b32 v253, s30, 26
	v_writelane_b32 v253, s31, 27
	v_writelane_b32 v253, s32, 28
	v_writelane_b32 v253, s33, 29
	v_writelane_b32 v253, s34, 30
	v_writelane_b32 v253, s35, 31
	v_writelane_b32 v253, s36, 32
	v_writelane_b32 v253, s37, 33
	v_writelane_b32 v253, s38, 34
	v_writelane_b32 v253, s39, 35
	v_writelane_b32 v253, s40, 36
	v_writelane_b32 v253, s41, 37
	v_writelane_b32 v253, s42, 38
	v_writelane_b32 v253, s43, 39
	v_writelane_b32 v253, s44, 40
	s_mov_b64 s[18:19], s[92:93]
	s_load_dwordx2 s[16:17], s[92:93], 0xf8
	s_lshl_b32 s0, s79, 3
	s_lshl_b32 s3, s79, 6
	s_and_b32 s3, s3, 0xc0
	s_and_b32 s12, s0, 0x1fffffe0
	s_or_b32 s6, s0, 24
	s_waitcnt lgkmcnt(0)
	s_add_u32 s22, s16, 0x1400000
	s_addc_u32 s23, s17, 0
	s_or_b32 s7, s0, 1
	s_add_u32 s24, s16, 0xe00000
	s_movk_i32 s4, 0xc0
	v_and_b32_e32 v5, 32, v164
	s_addc_u32 s25, s17, 0
	v_lshlrev_b32_e32 v3, 2, v148
	v_and_or_b32 v45, v150, s4, v5
	s_add_u32 s26, s16, 0x300000
	v_lshrrev_b32_e32 v5, 5, v148
	v_and_b32_e32 v4, 28, v3
	v_or_b32_e32 v43, s3, v148
	s_addc_u32 s27, s17, 0
	v_mul_u32_u24_e32 v5, 0xb00, v5
	s_movk_i32 s4, 0x60
	s_add_i32 s13, s2, 356
	s_lshl_b32 s13, s13, 4
	v_and_b32_e32 v1, 0xe0, v3
	s_mov_b32 s21, 0
	v_mov_b32_e32 v2, 0
	v_lshl_add_u32 v42, v148, 4, 0
	s_mul_i32 s1, s79, 0x2080
	v_lshl_add_u32 v44, v43, 2, 0
	s_mul_i32 s3, s12, 0x410
	s_mulk_i32 s6, 0x410
	s_mulk_i32 s7, 0x410
	v_and_or_b32 v46, v3, s4, v5
	v_cmp_gt_u32_e64 s[4:5], 8, v4
	s_add_i32 s30, s13, 0xffffdf00
	s_movk_i32 s31, 0x480
	s_add_i32 s33, s2, 356
	s_lshl_b32 s33, s33, 6
	s_movk_i32 s34, 0x1200
	s_movk_i32 s35, 0xd00
	s_movk_i32 s36, 0x7fff
	s_mov_b32 s37, 0xffff0000
	s_lshl_b32 s20, s12, 1
	v_lshlrev_b32_e32 v38, 2, v4
	v_mov_b32_e32 v47, 0x3420
	v_mov_b32_e32 v48, 0x5800
	s_add_i32 s38, s2, 356
	s_branch .Lp1cv_6

; #define LAS __attribute__((address_space(3)))
; __device__ __forceinline__ void convert_tile(const float* __restrict__ W, int K, int ldn, const float* __restrict__ gain, bf16_t* WT, int pn, int k0, int kind, LAS unsigned char* lds, int wave, int lane) {
;     ...
;     u32x4* dst = (u32x4*)(WT + (size_t)(256 * pn + n) * K + k0 + 32 * hf);
; #pragma unroll
;     for (int j = 0; j < 4; ++j) dst[j] = o[j];
; }
; __device__ __forceinline__ void convert_weights(CArgsP a, LAS unsigned char* lds, int wave, int lane, int which, int gb, int NGB) {
;     unsigned char* ws = a->ws;
;     constexpr int I0 = 22 * 16, I1 = 4 * 44, I2 = 14 * 16, I3 = 4 * 16;
;     const int NIT = which == 0 ? I0 + I1 + I2 : I0 + I1 + I3;
;     for (int it = gb; it < NIT; it += NGB) {
.Lp1cv_5:
	v_mov_b32_e32 v23, v2
	v_lshl_add_u64 v[20:21], v[22:23], 1, v[20:21]
	s_addk_i32 s38, 0x48
	s_add_i32 s30, s30, s31
	s_add_i32 s33, s33, s34
	v_lshl_add_u64 v[20:21], v[20:21], 0, s[20:21]
	s_cmpk_lt_i32 s38, 0x2f0
	global_store_dwordx4 v[20:21], v[4:7], off
	global_store_dwordx4 v[20:21], v[8:11], off offset:16
	global_store_dwordx4 v[20:21], v[12:15], off offset:32
	global_store_dwordx4 v[20:21], v[16:19], off offset:48
	s_cbranch_scc0 .Lp1cv_done
